# GU epilogue: two row blocks interleaved for more ILP, bf16 pack in place
# baseline (speedup 1.0000x reference)
; __device__ __forceinline__ unsigned cvt_pk_bf16(float lo, float hi) { unsigned r; asm volatile("v_cvt_pk_bf16_f32 %0, %1, %2" : "=v"(r) : "v"(lo), "v"(hi)); return r; }
; __device__ __forceinline__ void row_rs8(const float* SS, int row0, int fq, float (&rs)[2][4]) {
;     f32x4 a[2][4];
; #pragma unroll
;     for (int ai = 0; ai < 2; ++ai)
; #pragma unroll
;         for (int m = 0; m < 4; ++m) a[ai][m] = *(const f32x4*)(SS + (size_t)(row0 + ai * HALF + m * 16) * 16 + 4 * fq);
; #pragma unroll
;     for (int ai = 0; ai < 2; ++ai)
; #pragma unroll
;         for (int m = 0; m < 4; ++m) { float s = (a[ai][m][0] + a[ai][m][1]) + (a[ai][m][2] + a[ai][m][3]); s += __shfl_xor(s, 16); s += xhalf(s, fq >= 2); rs[ai][m] = __builtin_amdgcn_rsqf(s * (1.0f / 1024.0f) + RMS_EPS); }
; }
; __device__ __forceinline__ float silu_f(float g) { return g * __builtin_amdgcn_rcpf(1.0f + __expf(-g)); }
;     __device__ __forceinline__ void operator()(const f32x4 (&acc)[2][2][4][2], const Unit& u, int wr, int wc, int fr, int fq) const {
;         const int row0 = u.pm * BM + wr * 64 + fr, col0 = u.pn * 128 + wc * 32 + 8 * fq;
;         float rs8[2][4]; row_rs8(SS, row0, fq, rs8);
; #pragma unroll
;         for (int ai = 0; ai < 2; ++ai)
; #pragma unroll
;             for (int m = 0; m < 4; ++m) {
;                 const int row = row0 + ai * HALF + m * 16; const float rs = rs8[ai][m];
;                 float o[8];
; #pragma unroll
;                 for (int n = 0; n < 2; ++n)
; #pragma unroll
;                     for (int j = 0; j < 4; ++j) { const float g = acc[ai][0][m][n][j] * rs, uu = acc[ai][1][m][n][j] * rs; o[4 * n + j] = silu_f(g) * uu; }
;                 u32x4 w; w.x = cvt_pk_bf16(o[0], o[1]); w.y = cvt_pk_bf16(o[2], o[3]); w.z = cvt_pk_bf16(o[4], o[5]); w.w = cvt_pk_bf16(o[6], o[7]);
;                 *(u32x4*)(ACT + (size_t)row * 2816 + col0) = w;
.LBB0_500:
	v_add_u32_e32 v152, s37, v169
	v_ashrrev_i32_e32 v153, 31, v152
	v_or_b32_e32 v148, 16, v152
	v_lshlrev_b64 v[128:129], 6, v[152:153]
	v_ashrrev_i32_e32 v149, 31, v148
	v_or_b32_e32 v144, 32, v152
	v_add_u32_e32 v132, 0x90, v152
	v_lshl_add_u64 v[128:129], v[176:177], 0, v[128:129]
	v_lshlrev_b64 v[130:131], 6, v[148:149]
	v_ashrrev_i32_e32 v145, 31, v144
	v_ashrrev_i32_e32 v133, 31, v132
	v_lshl_add_u64 v[130:131], v[176:177], 0, v[130:131]
	global_load_dwordx4 v[140:143], v[128:129], off
	global_load_dwordx4 v[156:159], v[130:131], off
	v_lshlrev_b64 v[128:129], 6, v[144:145]
	v_or_b32_e32 v138, 48, v152
	v_lshlrev_b64 v[136:137], 6, v[132:133]
	v_lshl_add_u64 v[128:129], v[176:177], 0, v[128:129]
	v_ashrrev_i32_e32 v139, 31, v138
	v_lshl_add_u64 v[136:137], v[176:177], 0, v[136:137]
	global_load_dwordx4 v[186:189], v[128:129], off
	global_load_dwordx4 v[198:201], v[136:137], off
	v_lshlrev_b64 v[128:129], 6, v[138:139]
	v_lshl_add_u64 v[128:129], v[176:177], 0, v[128:129]
	global_load_dwordx4 v[190:193], v[128:129], off
	v_add_u32_e32 v134, 0x80, v152
	v_ashrrev_i32_e32 v135, 31, v134
	v_lshlrev_b64 v[128:129], 6, v[134:135]
	v_lshl_add_u64 v[128:129], v[176:177], 0, v[128:129]
	global_load_dwordx4 v[194:197], v[128:129], off
	v_add_u32_e32 v130, 0xa0, v152
	v_and_b32_e32 v129, 64, v225
	v_add_u32_e32 v128, 0xb0, v152
	v_ashrrev_i32_e32 v131, 31, v130
	v_add_u32_e32 v139, 64, v129
	v_ashrrev_i32_e32 v129, 31, v128
	v_lshlrev_b64 v[136:137], 6, v[130:131]
	v_lshlrev_b64 v[146:147], 6, v[128:129]
	v_lshl_add_u64 v[136:137], v[176:177], 0, v[136:137]
	v_lshl_add_u64 v[146:147], v[176:177], 0, v[146:147]
	global_load_dwordx4 v[202:205], v[136:137], off
	global_load_dwordx4 v[214:217], v[146:147], off
	v_xor_b32_e32 v135, 16, v225
	v_cmp_lt_i32_e32 vcc, v135, v139
	v_lshl_or_b32 v154, s44, 7, v207
	v_ashrrev_i32_e32 v155, 31, v154
	v_cndmask_b32_e32 v133, v225, v135, vcc
	v_lshlrev_b32_e32 v129, 2, v133
	s_waitcnt vmcnt(0)
	v_add_f32_e32 v140, v140, v141
	v_add_f32_e32 v142, v142, v143
	v_add_f32_e32 v156, v156, v157
	v_add_f32_e32 v158, v158, v159
	v_add_f32_e32 v186, v186, v187
	v_add_f32_e32 v188, v188, v189
	v_add_f32_e32 v190, v190, v191
	v_add_f32_e32 v192, v192, v193
	v_add_f32_e32 v194, v194, v195
	v_add_f32_e32 v196, v196, v197
	v_add_f32_e32 v198, v198, v199
	v_add_f32_e32 v200, v200, v201
	v_add_f32_e32 v202, v202, v203
	v_add_f32_e32 v204, v204, v205
	v_add_f32_e32 v214, v214, v215
	v_add_f32_e32 v216, v216, v217
	v_add_f32_e32 v140, v140, v142
	v_add_f32_e32 v156, v156, v158
	v_add_f32_e32 v186, v186, v188
	v_add_f32_e32 v190, v190, v192
	v_add_f32_e32 v194, v194, v196
	v_add_f32_e32 v198, v198, v200
	v_add_f32_e32 v202, v202, v204
	v_add_f32_e32 v214, v214, v216
	ds_bpermute_b32 v143, v129, v140
	ds_bpermute_b32 v159, v129, v156
	ds_bpermute_b32 v189, v129, v186
	ds_bpermute_b32 v193, v129, v190
	ds_bpermute_b32 v197, v129, v194
	ds_bpermute_b32 v201, v129, v198
	ds_bpermute_b32 v205, v129, v202
	ds_bpermute_b32 v217, v129, v214
	v_mov_b64_e32 v[226:227], s[26:27]
	v_lshlrev_b64 v[228:229], 1, v[154:155]
	s_waitcnt lgkmcnt(0)
	v_add_f32_e32 v140, v140, v143
	v_add_f32_e32 v156, v156, v159
	v_add_f32_e32 v186, v186, v189
	v_add_f32_e32 v190, v190, v193
	v_add_f32_e32 v194, v194, v197
	v_add_f32_e32 v198, v198, v201
	v_add_f32_e32 v202, v202, v205
	v_add_f32_e32 v214, v214, v217
	v_mov_b32_e32 v141, v140
	v_mov_b32_e32 v142, v140
	v_mov_b32_e32 v157, v156
	v_mov_b32_e32 v158, v156
	v_mov_b32_e32 v187, v186
	v_mov_b32_e32 v188, v186
	v_mov_b32_e32 v191, v190
	v_mov_b32_e32 v192, v190
	v_mov_b32_e32 v195, v194
	v_mov_b32_e32 v196, v194
	v_mov_b32_e32 v199, v198
	v_mov_b32_e32 v200, v198
	v_mov_b32_e32 v203, v202
	v_mov_b32_e32 v204, v202
	v_mov_b32_e32 v215, v214
	v_mov_b32_e32 v216, v214
	s_nop 1
	v_permlane32_swap_b32_e32 v141, v142
	v_permlane32_swap_b32_e32 v157, v158
	v_permlane32_swap_b32_e32 v187, v188
	v_permlane32_swap_b32_e32 v191, v192
	v_permlane32_swap_b32_e32 v195, v196
	v_permlane32_swap_b32_e32 v199, v200
	v_permlane32_swap_b32_e32 v203, v204
	v_permlane32_swap_b32_e32 v215, v216
	v_cndmask_b32_e64 v141, v142, v141, s[6:7]
	v_cndmask_b32_e64 v157, v158, v157, s[6:7]
	v_cndmask_b32_e64 v187, v188, v187, s[6:7]
	v_cndmask_b32_e64 v191, v192, v191, s[6:7]
	v_cndmask_b32_e64 v195, v196, v195, s[6:7]
	v_cndmask_b32_e64 v199, v200, v199, s[6:7]
	v_cndmask_b32_e64 v203, v204, v203, s[6:7]
	v_cndmask_b32_e64 v215, v216, v215, s[6:7]
	v_add_f32_e32 v140, v140, v141
	v_add_f32_e32 v156, v156, v157
	v_add_f32_e32 v186, v186, v187
	v_add_f32_e32 v190, v190, v191
	v_add_f32_e32 v194, v194, v195
	v_add_f32_e32 v198, v198, v199
	v_add_f32_e32 v202, v202, v203
	v_add_f32_e32 v214, v214, v215
	v_fmamk_f32 v140, v140, 0x3a800000, v209
	v_fmamk_f32 v156, v156, 0x3a800000, v209
	v_fmamk_f32 v186, v186, 0x3a800000, v209
	v_fmamk_f32 v190, v190, 0x3a800000, v209
	v_fmamk_f32 v194, v194, 0x3a800000, v209
	v_fmamk_f32 v198, v198, 0x3a800000, v209
	v_fmamk_f32 v202, v202, 0x3a800000, v209
	v_fmamk_f32 v214, v214, 0x3a800000, v209
	v_rsq_f32_e32 v140, v140
	v_rsq_f32_e32 v156, v156
	v_rsq_f32_e32 v186, v186
	v_rsq_f32_e32 v190, v190
	v_rsq_f32_e32 v194, v194
	v_rsq_f32_e32 v198, v198
	v_rsq_f32_e32 v202, v202
	v_rsq_f32_e32 v214, v214
	v_mov_b32_e32 v216, 0xbfb8aa3b
	v_mov_b32_e32 v204, 1.0
	v_pk_mul_f32 v[124:125], v[124:125], v[140:141] op_sel_hi:[1,0]
	v_pk_mul_f32 v[126:127], v[126:127], v[140:141] op_sel_hi:[1,0]
	v_pk_mul_f32 v[116:117], v[116:117], v[140:141] op_sel_hi:[1,0]
	v_pk_mul_f32 v[118:119], v[118:119], v[140:141] op_sel_hi:[1,0]
	v_pk_mul_f32 v[108:109], v[108:109], v[156:157] op_sel_hi:[1,0]
; __device__ __forceinline__ unsigned cvt_pk_bf16(float lo, float hi) { unsigned r; asm volatile("v_cvt_pk_bf16_f32 %0, %1, %2" : "=v"(r) : "v"(lo), "v"(hi)); return r; }
; __device__ __forceinline__ float silu_f(float g) { return g * __builtin_amdgcn_rcpf(1.0f + __expf(-g)); }
;     __device__ __forceinline__ void operator()(const f32x4 (&acc)[2][2][4][2], const Unit& u, int wr, int wc, int fr, int fq) const {
;         const int row0 = u.pm * BM + wr * 64 + fr, col0 = u.pn * 128 + wc * 32 + 8 * fq;
;         float rs8[2][4]; row_rs8(SS, row0, fq, rs8);
; #pragma unroll
;         for (int ai = 0; ai < 2; ++ai)
; #pragma unroll
;             for (int m = 0; m < 4; ++m) {
;                 const int row = row0 + ai * HALF + m * 16; const float rs = rs8[ai][m];
;                 float o[8];
; #pragma unroll
;                 for (int n = 0; n < 2; ++n)
; #pragma unroll
;                     for (int j = 0; j < 4; ++j) { const float g = acc[ai][0][m][n][j] * rs, uu = acc[ai][1][m][n][j] * rs; o[4 * n + j] = silu_f(g) * uu; }
;                 u32x4 w; w.x = cvt_pk_bf16(o[0], o[1]); w.y = cvt_pk_bf16(o[2], o[3]); w.z = cvt_pk_bf16(o[4], o[5]); w.w = cvt_pk_bf16(o[6], o[7]);
;                 *(u32x4*)(ACT + (size_t)row * 2816 + col0) = w;
;                 asm volatile("" ::: "memory");
;             }
	v_pk_mul_f32 v[110:111], v[110:111], v[156:157] op_sel_hi:[1,0]
	v_pk_mul_f32 v[100:101], v[100:101], v[156:157] op_sel_hi:[1,0]
	v_pk_mul_f32 v[102:103], v[102:103], v[156:157] op_sel_hi:[1,0]
	v_pk_mul_f32 v[142:143], v[124:125], v[216:217] op_sel_hi:[1,0]
	v_pk_mul_f32 v[158:159], v[126:127], v[216:217] op_sel_hi:[1,0]
	v_pk_mul_f32 v[188:189], v[116:117], v[216:217] op_sel_hi:[1,0]
	v_pk_mul_f32 v[192:193], v[118:119], v[216:217] op_sel_hi:[1,0]
	v_pk_mul_f32 v[196:197], v[108:109], v[216:217] op_sel_hi:[1,0]
	v_pk_mul_f32 v[200:201], v[110:111], v[216:217] op_sel_hi:[1,0]
	v_pk_mul_f32 v[146:147], v[100:101], v[216:217] op_sel_hi:[1,0]
	v_pk_mul_f32 v[150:151], v[102:103], v[216:217] op_sel_hi:[1,0]
	v_exp_f32_e32 v142, v142
	v_exp_f32_e32 v143, v143
	v_exp_f32_e32 v158, v158
	v_exp_f32_e32 v159, v159
	v_exp_f32_e32 v188, v188
	v_exp_f32_e32 v189, v189
	v_exp_f32_e32 v192, v192
	v_exp_f32_e32 v193, v193
	v_exp_f32_e32 v196, v196
	v_exp_f32_e32 v197, v197
	v_exp_f32_e32 v200, v200
	v_exp_f32_e32 v201, v201
	v_exp_f32_e32 v146, v146
	v_exp_f32_e32 v147, v147
	v_exp_f32_e32 v150, v150
	v_exp_f32_e32 v151, v151
	v_pk_mul_f32 v[120:121], v[120:121], v[140:141] op_sel_hi:[1,0]
	v_pk_mul_f32 v[122:123], v[122:123], v[140:141] op_sel_hi:[1,0]
	v_pk_mul_f32 v[112:113], v[112:113], v[140:141] op_sel_hi:[1,0]
	v_pk_mul_f32 v[114:115], v[114:115], v[140:141] op_sel_hi:[1,0]
	v_pk_mul_f32 v[104:105], v[104:105], v[156:157] op_sel_hi:[1,0]
	v_pk_mul_f32 v[106:107], v[106:107], v[156:157] op_sel_hi:[1,0]
	v_pk_mul_f32 v[96:97], v[96:97], v[156:157] op_sel_hi:[1,0]
	v_pk_mul_f32 v[98:99], v[98:99], v[156:157] op_sel_hi:[1,0]
	v_pk_add_f32 v[142:143], v[142:143], v[204:205] op_sel_hi:[1,0]
	v_pk_add_f32 v[158:159], v[158:159], v[204:205] op_sel_hi:[1,0]
	v_pk_add_f32 v[188:189], v[188:189], v[204:205] op_sel_hi:[1,0]
	v_pk_add_f32 v[192:193], v[192:193], v[204:205] op_sel_hi:[1,0]
	v_pk_add_f32 v[196:197], v[196:197], v[204:205] op_sel_hi:[1,0]
	v_pk_add_f32 v[200:201], v[200:201], v[204:205] op_sel_hi:[1,0]
	v_pk_add_f32 v[146:147], v[146:147], v[204:205] op_sel_hi:[1,0]
	v_pk_add_f32 v[150:151], v[150:151], v[204:205] op_sel_hi:[1,0]
	v_rcp_f32_e32 v142, v142
	v_rcp_f32_e32 v143, v143
	v_rcp_f32_e32 v158, v158
	v_rcp_f32_e32 v159, v159
	v_rcp_f32_e32 v188, v188
	v_rcp_f32_e32 v189, v189
	v_rcp_f32_e32 v192, v192
	v_rcp_f32_e32 v193, v193
	v_rcp_f32_e32 v196, v196
	v_rcp_f32_e32 v197, v197
	v_rcp_f32_e32 v200, v200
	v_rcp_f32_e32 v201, v201
	v_rcp_f32_e32 v146, v146
	v_rcp_f32_e32 v147, v147
	v_rcp_f32_e32 v150, v150
	v_rcp_f32_e32 v151, v151
	v_mad_i64_i32 v[230:231], s[10:11], v152, s53, v[226:227]
	v_lshl_add_u64 v[230:231], v[230:231], 0, v[228:229]
	v_mad_i64_i32 v[232:233], s[10:11], v148, s53, v[226:227]
	v_lshl_add_u64 v[232:233], v[232:233], 0, v[228:229]
	v_pk_mul_f32 v[142:143], v[124:125], v[142:143]
	v_pk_mul_f32 v[158:159], v[126:127], v[158:159]
	v_pk_mul_f32 v[188:189], v[116:117], v[188:189]
	v_pk_mul_f32 v[192:193], v[118:119], v[192:193]
	v_pk_mul_f32 v[196:197], v[108:109], v[196:197]
	v_pk_mul_f32 v[200:201], v[110:111], v[200:201]
	v_pk_mul_f32 v[146:147], v[100:101], v[146:147]
	v_pk_mul_f32 v[150:151], v[102:103], v[150:151]
	v_pk_mul_f32 v[120:121], v[120:121], v[142:143]
	v_pk_mul_f32 v[122:123], v[122:123], v[158:159]
	v_pk_mul_f32 v[112:113], v[112:113], v[188:189]
	v_pk_mul_f32 v[114:115], v[114:115], v[192:193]
	v_pk_mul_f32 v[104:105], v[104:105], v[196:197]
	v_pk_mul_f32 v[106:107], v[106:107], v[200:201]
	v_pk_mul_f32 v[96:97], v[96:97], v[146:147]
	v_pk_mul_f32 v[98:99], v[98:99], v[150:151]
	v_cvt_pk_bf16_f32 v120, v120, v121
	v_cvt_pk_bf16_f32 v121, v122, v123
	v_cvt_pk_bf16_f32 v122, v112, v113
	v_cvt_pk_bf16_f32 v123, v114, v115
	v_cvt_pk_bf16_f32 v104, v104, v105
	v_cvt_pk_bf16_f32 v105, v106, v107
	v_cvt_pk_bf16_f32 v106, v96, v97
	v_cvt_pk_bf16_f32 v107, v98, v99
	global_store_dwordx4 v[230:231], v[120:123], off
	global_store_dwordx4 v[232:233], v[104:107], off
	v_pk_mul_f32 v[92:93], v[92:93], v[186:187] op_sel_hi:[1,0]
	v_pk_mul_f32 v[94:95], v[94:95], v[186:187] op_sel_hi:[1,0]
	v_pk_mul_f32 v[84:85], v[84:85], v[186:187] op_sel_hi:[1,0]
	v_pk_mul_f32 v[86:87], v[86:87], v[186:187] op_sel_hi:[1,0]
	v_pk_mul_f32 v[76:77], v[76:77], v[190:191] op_sel_hi:[1,0]
	v_pk_mul_f32 v[78:79], v[78:79], v[190:191] op_sel_hi:[1,0]
	v_pk_mul_f32 v[68:69], v[68:69], v[190:191] op_sel_hi:[1,0]
	v_pk_mul_f32 v[70:71], v[70:71], v[190:191] op_sel_hi:[1,0]
	v_pk_mul_f32 v[142:143], v[92:93], v[216:217] op_sel_hi:[1,0]
	v_pk_mul_f32 v[158:159], v[94:95], v[216:217] op_sel_hi:[1,0]
	v_pk_mul_f32 v[188:189], v[84:85], v[216:217] op_sel_hi:[1,0]
	v_pk_mul_f32 v[192:193], v[86:87], v[216:217] op_sel_hi:[1,0]
	v_pk_mul_f32 v[196:197], v[76:77], v[216:217] op_sel_hi:[1,0]
	v_pk_mul_f32 v[200:201], v[78:79], v[216:217] op_sel_hi:[1,0]
	v_pk_mul_f32 v[146:147], v[68:69], v[216:217] op_sel_hi:[1,0]
	v_pk_mul_f32 v[150:151], v[70:71], v[216:217] op_sel_hi:[1,0]
	v_exp_f32_e32 v142, v142
	v_exp_f32_e32 v143, v143
	v_exp_f32_e32 v158, v158
	v_exp_f32_e32 v159, v159
	v_exp_f32_e32 v188, v188
	v_exp_f32_e32 v189, v189
	v_exp_f32_e32 v192, v192
	v_exp_f32_e32 v193, v193
	v_exp_f32_e32 v196, v196
	v_exp_f32_e32 v197, v197
	v_exp_f32_e32 v200, v200
	v_exp_f32_e32 v201, v201
	v_exp_f32_e32 v146, v146
	v_exp_f32_e32 v147, v147
	v_exp_f32_e32 v150, v150
	v_exp_f32_e32 v151, v151
	v_pk_mul_f32 v[88:89], v[88:89], v[186:187] op_sel_hi:[1,0]
	v_pk_mul_f32 v[90:91], v[90:91], v[186:187] op_sel_hi:[1,0]
	v_pk_mul_f32 v[80:81], v[80:81], v[186:187] op_sel_hi:[1,0]
	v_pk_mul_f32 v[82:83], v[82:83], v[186:187] op_sel_hi:[1,0]
; __device__ __forceinline__ unsigned cvt_pk_bf16(float lo, float hi) { unsigned r; asm volatile("v_cvt_pk_bf16_f32 %0, %1, %2" : "=v"(r) : "v"(lo), "v"(hi)); return r; }
; __device__ __forceinline__ float silu_f(float g) { return g * __builtin_amdgcn_rcpf(1.0f + __expf(-g)); }
;     __device__ __forceinline__ void operator()(const f32x4 (&acc)[2][2][4][2], const Unit& u, int wr, int wc, int fr, int fq) const {
;         const int row0 = u.pm * BM + wr * 64 + fr, col0 = u.pn * 128 + wc * 32 + 8 * fq;
;         float rs8[2][4]; row_rs8(SS, row0, fq, rs8);
; #pragma unroll
;         for (int ai = 0; ai < 2; ++ai)
; #pragma unroll
;             for (int m = 0; m < 4; ++m) {
;                 const int row = row0 + ai * HALF + m * 16; const float rs = rs8[ai][m];
;                 float o[8];
; #pragma unroll
;                 for (int n = 0; n < 2; ++n)
; #pragma unroll
;                     for (int j = 0; j < 4; ++j) { const float g = acc[ai][0][m][n][j] * rs, uu = acc[ai][1][m][n][j] * rs; o[4 * n + j] = silu_f(g) * uu; }
;                 u32x4 w; w.x = cvt_pk_bf16(o[0], o[1]); w.y = cvt_pk_bf16(o[2], o[3]); w.z = cvt_pk_bf16(o[4], o[5]); w.w = cvt_pk_bf16(o[6], o[7]);
;                 *(u32x4*)(ACT + (size_t)row * 2816 + col0) = w;
;                 asm volatile("" ::: "memory");
;             }
	v_pk_mul_f32 v[72:73], v[72:73], v[190:191] op_sel_hi:[1,0]
	v_pk_mul_f32 v[74:75], v[74:75], v[190:191] op_sel_hi:[1,0]
	v_pk_mul_f32 v[64:65], v[64:65], v[190:191] op_sel_hi:[1,0]
	v_pk_mul_f32 v[66:67], v[66:67], v[190:191] op_sel_hi:[1,0]
	v_pk_add_f32 v[142:143], v[142:143], v[204:205] op_sel_hi:[1,0]
	v_pk_add_f32 v[158:159], v[158:159], v[204:205] op_sel_hi:[1,0]
	v_pk_add_f32 v[188:189], v[188:189], v[204:205] op_sel_hi:[1,0]
	v_pk_add_f32 v[192:193], v[192:193], v[204:205] op_sel_hi:[1,0]
	v_pk_add_f32 v[196:197], v[196:197], v[204:205] op_sel_hi:[1,0]
	v_pk_add_f32 v[200:201], v[200:201], v[204:205] op_sel_hi:[1,0]
	v_pk_add_f32 v[146:147], v[146:147], v[204:205] op_sel_hi:[1,0]
	v_pk_add_f32 v[150:151], v[150:151], v[204:205] op_sel_hi:[1,0]
	v_rcp_f32_e32 v142, v142
	v_rcp_f32_e32 v143, v143
	v_rcp_f32_e32 v158, v158
	v_rcp_f32_e32 v159, v159
	v_rcp_f32_e32 v188, v188
	v_rcp_f32_e32 v189, v189
	v_rcp_f32_e32 v192, v192
	v_rcp_f32_e32 v193, v193
	v_rcp_f32_e32 v196, v196
	v_rcp_f32_e32 v197, v197
	v_rcp_f32_e32 v200, v200
	v_rcp_f32_e32 v201, v201
	v_rcp_f32_e32 v146, v146
	v_rcp_f32_e32 v147, v147
	v_rcp_f32_e32 v150, v150
	v_rcp_f32_e32 v151, v151
	v_mad_i64_i32 v[230:231], s[10:11], v144, s53, v[226:227]
	v_lshl_add_u64 v[230:231], v[230:231], 0, v[228:229]
	v_mad_i64_i32 v[232:233], s[10:11], v138, s53, v[226:227]
	v_lshl_add_u64 v[232:233], v[232:233], 0, v[228:229]
	v_pk_mul_f32 v[142:143], v[92:93], v[142:143]
	v_pk_mul_f32 v[158:159], v[94:95], v[158:159]
	v_pk_mul_f32 v[188:189], v[84:85], v[188:189]
	v_pk_mul_f32 v[192:193], v[86:87], v[192:193]
	v_pk_mul_f32 v[196:197], v[76:77], v[196:197]
	v_pk_mul_f32 v[200:201], v[78:79], v[200:201]
	v_pk_mul_f32 v[146:147], v[68:69], v[146:147]
	v_pk_mul_f32 v[150:151], v[70:71], v[150:151]
	v_pk_mul_f32 v[88:89], v[88:89], v[142:143]
	v_pk_mul_f32 v[90:91], v[90:91], v[158:159]
	v_pk_mul_f32 v[80:81], v[80:81], v[188:189]
	v_pk_mul_f32 v[82:83], v[82:83], v[192:193]
	v_pk_mul_f32 v[72:73], v[72:73], v[196:197]
	v_pk_mul_f32 v[74:75], v[74:75], v[200:201]
	v_pk_mul_f32 v[64:65], v[64:65], v[146:147]
	v_pk_mul_f32 v[66:67], v[66:67], v[150:151]
	v_cvt_pk_bf16_f32 v88, v88, v89
	v_cvt_pk_bf16_f32 v89, v90, v91
	v_cvt_pk_bf16_f32 v90, v80, v81
	v_cvt_pk_bf16_f32 v91, v82, v83
	v_cvt_pk_bf16_f32 v72, v72, v73
	v_cvt_pk_bf16_f32 v73, v74, v75
	v_cvt_pk_bf16_f32 v74, v64, v65
	v_cvt_pk_bf16_f32 v75, v66, v67
	global_store_dwordx4 v[230:231], v[88:91], off
	global_store_dwordx4 v[232:233], v[72:75], off
	v_pk_mul_f32 v[60:61], v[60:61], v[194:195] op_sel_hi:[1,0]
	v_pk_mul_f32 v[62:63], v[62:63], v[194:195] op_sel_hi:[1,0]
	v_pk_mul_f32 v[52:53], v[52:53], v[194:195] op_sel_hi:[1,0]
	v_pk_mul_f32 v[54:55], v[54:55], v[194:195] op_sel_hi:[1,0]
	v_pk_mul_f32 v[44:45], v[44:45], v[198:199] op_sel_hi:[1,0]
	v_pk_mul_f32 v[46:47], v[46:47], v[198:199] op_sel_hi:[1,0]
	v_pk_mul_f32 v[36:37], v[36:37], v[198:199] op_sel_hi:[1,0]
	v_pk_mul_f32 v[38:39], v[38:39], v[198:199] op_sel_hi:[1,0]
	v_pk_mul_f32 v[142:143], v[60:61], v[216:217] op_sel_hi:[1,0]
	v_pk_mul_f32 v[158:159], v[62:63], v[216:217] op_sel_hi:[1,0]
	v_pk_mul_f32 v[188:189], v[52:53], v[216:217] op_sel_hi:[1,0]
	v_pk_mul_f32 v[192:193], v[54:55], v[216:217] op_sel_hi:[1,0]
	v_pk_mul_f32 v[196:197], v[44:45], v[216:217] op_sel_hi:[1,0]
	v_pk_mul_f32 v[200:201], v[46:47], v[216:217] op_sel_hi:[1,0]
	v_pk_mul_f32 v[146:147], v[36:37], v[216:217] op_sel_hi:[1,0]
	v_pk_mul_f32 v[150:151], v[38:39], v[216:217] op_sel_hi:[1,0]
	v_exp_f32_e32 v142, v142
	v_exp_f32_e32 v143, v143
	v_exp_f32_e32 v158, v158
	v_exp_f32_e32 v159, v159
	v_exp_f32_e32 v188, v188
	v_exp_f32_e32 v189, v189
	v_exp_f32_e32 v192, v192
	v_exp_f32_e32 v193, v193
	v_exp_f32_e32 v196, v196
	v_exp_f32_e32 v197, v197
	v_exp_f32_e32 v200, v200
	v_exp_f32_e32 v201, v201
	v_exp_f32_e32 v146, v146
	v_exp_f32_e32 v147, v147
	v_exp_f32_e32 v150, v150
	v_exp_f32_e32 v151, v151
	v_pk_mul_f32 v[56:57], v[56:57], v[194:195] op_sel_hi:[1,0]
	v_pk_mul_f32 v[58:59], v[58:59], v[194:195] op_sel_hi:[1,0]
	v_pk_mul_f32 v[48:49], v[48:49], v[194:195] op_sel_hi:[1,0]
	v_pk_mul_f32 v[50:51], v[50:51], v[194:195] op_sel_hi:[1,0]
	v_pk_mul_f32 v[40:41], v[40:41], v[198:199] op_sel_hi:[1,0]
	v_pk_mul_f32 v[42:43], v[42:43], v[198:199] op_sel_hi:[1,0]
	v_pk_mul_f32 v[32:33], v[32:33], v[198:199] op_sel_hi:[1,0]
	v_pk_mul_f32 v[34:35], v[34:35], v[198:199] op_sel_hi:[1,0]
	v_pk_add_f32 v[142:143], v[142:143], v[204:205] op_sel_hi:[1,0]
	v_pk_add_f32 v[158:159], v[158:159], v[204:205] op_sel_hi:[1,0]
	v_pk_add_f32 v[188:189], v[188:189], v[204:205] op_sel_hi:[1,0]
	v_pk_add_f32 v[192:193], v[192:193], v[204:205] op_sel_hi:[1,0]
	v_pk_add_f32 v[196:197], v[196:197], v[204:205] op_sel_hi:[1,0]
	v_pk_add_f32 v[200:201], v[200:201], v[204:205] op_sel_hi:[1,0]
	v_pk_add_f32 v[146:147], v[146:147], v[204:205] op_sel_hi:[1,0]
	v_pk_add_f32 v[150:151], v[150:151], v[204:205] op_sel_hi:[1,0]
	v_rcp_f32_e32 v142, v142
	v_rcp_f32_e32 v143, v143
	v_rcp_f32_e32 v158, v158
	v_rcp_f32_e32 v159, v159
	v_rcp_f32_e32 v188, v188
	v_rcp_f32_e32 v189, v189
	v_rcp_f32_e32 v192, v192
	v_rcp_f32_e32 v193, v193
	v_rcp_f32_e32 v196, v196
	v_rcp_f32_e32 v197, v197
	v_rcp_f32_e32 v200, v200
	v_rcp_f32_e32 v201, v201
	v_rcp_f32_e32 v146, v146
	v_rcp_f32_e32 v147, v147
	v_rcp_f32_e32 v150, v150
	v_rcp_f32_e32 v151, v151
	v_mad_i64_i32 v[230:231], s[10:11], v134, s53, v[226:227]
	v_lshl_add_u64 v[230:231], v[230:231], 0, v[228:229]
; __device__ __forceinline__ unsigned cvt_pk_bf16(float lo, float hi) { unsigned r; asm volatile("v_cvt_pk_bf16_f32 %0, %1, %2" : "=v"(r) : "v"(lo), "v"(hi)); return r; }
; __device__ __forceinline__ float silu_f(float g) { return g * __builtin_amdgcn_rcpf(1.0f + __expf(-g)); }
;     __device__ __forceinline__ void operator()(const f32x4 (&acc)[2][2][4][2], const Unit& u, int wr, int wc, int fr, int fq) const {
;         const int row0 = u.pm * BM + wr * 64 + fr, col0 = u.pn * 128 + wc * 32 + 8 * fq;
;         float rs8[2][4]; row_rs8(SS, row0, fq, rs8);
; #pragma unroll
;         for (int ai = 0; ai < 2; ++ai)
; #pragma unroll
;             for (int m = 0; m < 4; ++m) {
;                 const int row = row0 + ai * HALF + m * 16; const float rs = rs8[ai][m];
;                 float o[8];
; #pragma unroll
;                 for (int n = 0; n < 2; ++n)
; #pragma unroll
;                     for (int j = 0; j < 4; ++j) { const float g = acc[ai][0][m][n][j] * rs, uu = acc[ai][1][m][n][j] * rs; o[4 * n + j] = silu_f(g) * uu; }
;                 u32x4 w; w.x = cvt_pk_bf16(o[0], o[1]); w.y = cvt_pk_bf16(o[2], o[3]); w.z = cvt_pk_bf16(o[4], o[5]); w.w = cvt_pk_bf16(o[6], o[7]);
;                 *(u32x4*)(ACT + (size_t)row * 2816 + col0) = w;
;                 asm volatile("" ::: "memory");
;             }
	v_mad_i64_i32 v[232:233], s[10:11], v132, s53, v[226:227]
	v_lshl_add_u64 v[232:233], v[232:233], 0, v[228:229]
	v_pk_mul_f32 v[142:143], v[60:61], v[142:143]
	v_pk_mul_f32 v[158:159], v[62:63], v[158:159]
	v_pk_mul_f32 v[188:189], v[52:53], v[188:189]
	v_pk_mul_f32 v[192:193], v[54:55], v[192:193]
	v_pk_mul_f32 v[196:197], v[44:45], v[196:197]
	v_pk_mul_f32 v[200:201], v[46:47], v[200:201]
	v_pk_mul_f32 v[146:147], v[36:37], v[146:147]
	v_pk_mul_f32 v[150:151], v[38:39], v[150:151]
	v_pk_mul_f32 v[56:57], v[56:57], v[142:143]
	v_pk_mul_f32 v[58:59], v[58:59], v[158:159]
	v_pk_mul_f32 v[48:49], v[48:49], v[188:189]
	v_pk_mul_f32 v[50:51], v[50:51], v[192:193]
	v_pk_mul_f32 v[40:41], v[40:41], v[196:197]
	v_pk_mul_f32 v[42:43], v[42:43], v[200:201]
	v_pk_mul_f32 v[32:33], v[32:33], v[146:147]
	v_pk_mul_f32 v[34:35], v[34:35], v[150:151]
	v_cvt_pk_bf16_f32 v56, v56, v57
	v_cvt_pk_bf16_f32 v57, v58, v59
	v_cvt_pk_bf16_f32 v58, v48, v49
	v_cvt_pk_bf16_f32 v59, v50, v51
	v_cvt_pk_bf16_f32 v40, v40, v41
	v_cvt_pk_bf16_f32 v41, v42, v43
	v_cvt_pk_bf16_f32 v42, v32, v33
	v_cvt_pk_bf16_f32 v43, v34, v35
	global_store_dwordx4 v[230:231], v[56:59], off
	global_store_dwordx4 v[232:233], v[40:43], off
	v_pk_mul_f32 v[28:29], v[28:29], v[202:203] op_sel_hi:[1,0]
	v_pk_mul_f32 v[30:31], v[30:31], v[202:203] op_sel_hi:[1,0]
	v_pk_mul_f32 v[20:21], v[20:21], v[202:203] op_sel_hi:[1,0]
	v_pk_mul_f32 v[22:23], v[22:23], v[202:203] op_sel_hi:[1,0]
	v_pk_mul_f32 v[12:13], v[12:13], v[214:215] op_sel_hi:[1,0]
	v_pk_mul_f32 v[14:15], v[14:15], v[214:215] op_sel_hi:[1,0]
	v_pk_mul_f32 v[4:5], v[4:5], v[214:215] op_sel_hi:[1,0]
	v_pk_mul_f32 v[6:7], v[6:7], v[214:215] op_sel_hi:[1,0]
	v_pk_mul_f32 v[142:143], v[28:29], v[216:217] op_sel_hi:[1,0]
	v_pk_mul_f32 v[158:159], v[30:31], v[216:217] op_sel_hi:[1,0]
	v_pk_mul_f32 v[188:189], v[20:21], v[216:217] op_sel_hi:[1,0]
	v_pk_mul_f32 v[192:193], v[22:23], v[216:217] op_sel_hi:[1,0]
	v_pk_mul_f32 v[196:197], v[12:13], v[216:217] op_sel_hi:[1,0]
	v_pk_mul_f32 v[200:201], v[14:15], v[216:217] op_sel_hi:[1,0]
	v_pk_mul_f32 v[146:147], v[4:5], v[216:217] op_sel_hi:[1,0]
	v_pk_mul_f32 v[150:151], v[6:7], v[216:217] op_sel_hi:[1,0]
	v_exp_f32_e32 v142, v142
	v_exp_f32_e32 v143, v143
	v_exp_f32_e32 v158, v158
	v_exp_f32_e32 v159, v159
	v_exp_f32_e32 v188, v188
	v_exp_f32_e32 v189, v189
	v_exp_f32_e32 v192, v192
	v_exp_f32_e32 v193, v193
	v_exp_f32_e32 v196, v196
	v_exp_f32_e32 v197, v197
	v_exp_f32_e32 v200, v200
	v_exp_f32_e32 v201, v201
	v_exp_f32_e32 v146, v146
	v_exp_f32_e32 v147, v147
	v_exp_f32_e32 v150, v150
	v_exp_f32_e32 v151, v151
	v_pk_mul_f32 v[24:25], v[24:25], v[202:203] op_sel_hi:[1,0]
	v_pk_mul_f32 v[26:27], v[26:27], v[202:203] op_sel_hi:[1,0]
	v_pk_mul_f32 v[16:17], v[16:17], v[202:203] op_sel_hi:[1,0]
	v_pk_mul_f32 v[18:19], v[18:19], v[202:203] op_sel_hi:[1,0]
	v_pk_mul_f32 v[8:9], v[8:9], v[214:215] op_sel_hi:[1,0]
	v_pk_mul_f32 v[10:11], v[10:11], v[214:215] op_sel_hi:[1,0]
	v_pk_mul_f32 v[0:1], v[0:1], v[214:215] op_sel_hi:[1,0]
	v_pk_mul_f32 v[2:3], v[2:3], v[214:215] op_sel_hi:[1,0]
	v_pk_add_f32 v[142:143], v[142:143], v[204:205] op_sel_hi:[1,0]
	v_pk_add_f32 v[158:159], v[158:159], v[204:205] op_sel_hi:[1,0]
	v_pk_add_f32 v[188:189], v[188:189], v[204:205] op_sel_hi:[1,0]
	v_pk_add_f32 v[192:193], v[192:193], v[204:205] op_sel_hi:[1,0]
	v_pk_add_f32 v[196:197], v[196:197], v[204:205] op_sel_hi:[1,0]
	v_pk_add_f32 v[200:201], v[200:201], v[204:205] op_sel_hi:[1,0]
	v_pk_add_f32 v[146:147], v[146:147], v[204:205] op_sel_hi:[1,0]
	v_pk_add_f32 v[150:151], v[150:151], v[204:205] op_sel_hi:[1,0]
	v_rcp_f32_e32 v142, v142
	v_rcp_f32_e32 v143, v143
	v_rcp_f32_e32 v158, v158
	v_rcp_f32_e32 v159, v159
	v_rcp_f32_e32 v188, v188
	v_rcp_f32_e32 v189, v189
	v_rcp_f32_e32 v192, v192
	v_rcp_f32_e32 v193, v193
	v_rcp_f32_e32 v196, v196
	v_rcp_f32_e32 v197, v197
	v_rcp_f32_e32 v200, v200
	v_rcp_f32_e32 v201, v201
	v_rcp_f32_e32 v146, v146
	v_rcp_f32_e32 v147, v147
	v_rcp_f32_e32 v150, v150
	v_rcp_f32_e32 v151, v151
	v_mad_i64_i32 v[230:231], s[10:11], v130, s53, v[226:227]
	v_lshl_add_u64 v[230:231], v[230:231], 0, v[228:229]
	v_mad_i64_i32 v[232:233], s[10:11], v128, s53, v[226:227]
	v_lshl_add_u64 v[232:233], v[232:233], 0, v[228:229]
	v_pk_mul_f32 v[142:143], v[28:29], v[142:143]
	v_pk_mul_f32 v[158:159], v[30:31], v[158:159]
	v_pk_mul_f32 v[188:189], v[20:21], v[188:189]
	v_pk_mul_f32 v[192:193], v[22:23], v[192:193]
	v_pk_mul_f32 v[196:197], v[12:13], v[196:197]
	v_pk_mul_f32 v[200:201], v[14:15], v[200:201]
	v_pk_mul_f32 v[146:147], v[4:5], v[146:147]
	v_pk_mul_f32 v[150:151], v[6:7], v[150:151]
	v_pk_mul_f32 v[24:25], v[24:25], v[142:143]
	v_pk_mul_f32 v[26:27], v[26:27], v[158:159]
	v_pk_mul_f32 v[16:17], v[16:17], v[188:189]
	v_pk_mul_f32 v[18:19], v[18:19], v[192:193]
	v_pk_mul_f32 v[8:9], v[8:9], v[196:197]
	v_pk_mul_f32 v[10:11], v[10:11], v[200:201]
	v_pk_mul_f32 v[0:1], v[0:1], v[146:147]
	v_pk_mul_f32 v[2:3], v[2:3], v[150:151]
	v_cvt_pk_bf16_f32 v24, v24, v25
	v_cvt_pk_bf16_f32 v25, v26, v27
	v_cvt_pk_bf16_f32 v26, v16, v17
	v_cvt_pk_bf16_f32 v27, v18, v19
	v_cvt_pk_bf16_f32 v8, v8, v9
	v_cvt_pk_bf16_f32 v9, v10, v11
	v_cvt_pk_bf16_f32 v10, v0, v1
	v_cvt_pk_bf16_f32 v11, v2, v3
	global_store_dwordx4 v[230:231], v[24:27], off
	global_store_dwordx4 v[232:233], v[8:11], off
	s_andn2_b64 vcc, exec, s[8:9]
	s_mov_b64 s[8:9], -1
	s_cbranch_vccnz .LBB0_488
	s_branch .LBB0_620
